# attention loop 2x unrolled, V tiles double-buffered in registers (2 iterations of load cover), merged LDS waits
# baseline (speedup 1.0000x reference)
.LBB0_1340:
	s_add_i32 s54, s0, 1
	v_mov_b32_e32 v174, v196
	s_mul_i32 s4, s52, 0x4800
	v_add_u32_e32 v234, s4, v195
	ds_read_b128 v[202:205], v174 offset:0
	ds_read_b128 v[206:209], v174 offset:32
	ds_read_b128 v[210:213], v174 offset:64
	ds_read_b128 v[214:217], v174 offset:96
	ds_read_b128 v[218:221], v174 offset:128
	ds_read_b128 v[222:225], v174 offset:160
	v_fma_f32 v64, v64, s84, -v199
	v_exp_f32_e32 v64, v64
	v_fma_f32 v65, v65, s84, -v199
	v_exp_f32_e32 v65, v65
	v_add_f32_e32 v200, v200, v64
	v_fma_f32 v66, v66, s84, -v199
	v_exp_f32_e32 v66, v66
	v_add_f32_e32 v200, v200, v65
	s_waitcnt lgkmcnt(4)
	v_mfma_f32_32x32x16_bf16 v[80:95], v[202:205], v[96:99], 0
	ds_read_b128 v[202:205], v174 offset:192
	v_fma_f32 v67, v67, s84, -v199
	v_exp_f32_e32 v67, v67
	v_add_f32_e32 v200, v200, v66
	v_fma_f32 v68, v68, s84, -v199
	v_mfma_f32_32x32x16_bf16 v[80:95], v[206:209], v[100:103], v[80:95]
	ds_read_b128 v[206:209], v174 offset:224
	v_exp_f32_e32 v68, v68
	v_add_f32_e32 v200, v200, v67
	v_fma_f32 v69, v69, s84, -v199
	v_exp_f32_e32 v69, v69
	s_waitcnt lgkmcnt(4)
	v_mfma_f32_32x32x16_bf16 v[80:95], v[210:213], v[104:107], v[80:95]
	ds_read_b128 v[210:213], v174 offset:256
	v_add_f32_e32 v200, v200, v68
	v_fma_f32 v70, v70, s84, -v199
	v_exp_f32_e32 v70, v70
	v_add_f32_e32 v200, v200, v69
	v_mfma_f32_32x32x16_bf16 v[80:95], v[214:217], v[108:111], v[80:95]
	ds_read_b128 v[214:217], v174 offset:288
	v_fma_f32 v71, v71, s84, -v199
	v_exp_f32_e32 v71, v71
	v_add_f32_e32 v200, v200, v70
	v_fma_f32 v72, v72, s84, -v199
	s_waitcnt lgkmcnt(4)
	v_mfma_f32_32x32x16_bf16 v[80:95], v[218:221], v[112:115], v[80:95]
	ds_read_b128 v[218:221], v174 offset:320
	v_exp_f32_e32 v72, v72
	v_add_f32_e32 v200, v200, v71
	v_fma_f32 v73, v73, s84, -v199
	v_exp_f32_e32 v73, v73
	v_mfma_f32_32x32x16_bf16 v[80:95], v[222:225], v[116:119], v[80:95]
	ds_read_b128 v[222:225], v174 offset:352
	v_add_f32_e32 v200, v200, v72
	v_fma_f32 v74, v74, s84, -v199
	v_exp_f32_e32 v74, v74
	v_add_f32_e32 v200, v200, v73
	s_waitcnt lgkmcnt(4)
	v_mfma_f32_32x32x16_bf16 v[80:95], v[202:205], v[120:123], v[80:95]
	ds_read_b128 v[164:167], v173 offset:0
	v_fma_f32 v75, v75, s84, -v199
	v_exp_f32_e32 v75, v75
	v_add_f32_e32 v200, v200, v74
	v_fma_f32 v76, v76, s84, -v199
	v_mfma_f32_32x32x16_bf16 v[80:95], v[206:209], v[124:127], v[80:95]
	ds_read_b128 v[168:171], v173 offset:4608
	v_exp_f32_e32 v76, v76
	v_add_f32_e32 v200, v200, v75
	v_fma_f32 v77, v77, s84, -v199
	v_exp_f32_e32 v77, v77
	s_waitcnt lgkmcnt(4)
	v_mfma_f32_32x32x16_bf16 v[80:95], v[210:213], v[160:163], v[80:95]
	ds_read_b128 v[176:179], v173 offset:9216
	v_add_f32_e32 v200, v200, v76
	v_fma_f32 v78, v78, s84, -v199
	v_exp_f32_e32 v78, v78
	v_add_f32_e32 v200, v200, v77
	v_mfma_f32_32x32x16_bf16 v[80:95], v[214:217], v[152:155], v[80:95]
	ds_read_b128 v[226:229], v173 offset:13824
	v_fma_f32 v79, v79, s84, -v199
	v_exp_f32_e32 v79, v79
	v_add_f32_e32 v200, v200, v78
	v_add_f32_e32 v200, v200, v79
	s_waitcnt lgkmcnt(4)
	v_mfma_f32_32x32x16_bf16 v[80:95], v[218:221], v[156:159], v[80:95]
	v_cvt_pk_bf16_f32 v64, v64, v65
	v_cvt_pk_bf16_f32 v65, v66, v67
	v_cvt_pk_bf16_f32 v66, v68, v69
	v_cvt_pk_bf16_f32 v67, v70, v71
	v_mfma_f32_32x32x16_bf16 v[80:95], v[222:225], v[148:151], v[80:95]
	v_cvt_pk_bf16_f32 v68, v72, v73
	v_cvt_pk_bf16_f32 v69, v74, v75
	v_cvt_pk_bf16_f32 v70, v76, v77
	v_cvt_pk_bf16_f32 v71, v78, v79
	s_waitcnt lgkmcnt(2)
	v_mfma_f32_32x32x16_bf16 v[48:63], v[164:167], v[64:67], v[48:63]
	ds_read_b128 v[164:167], v173 offset:32
	v_mfma_f32_32x32x16_bf16 v[32:47], v[168:171], v[64:67], v[32:47]
	ds_read_b128 v[168:171], v173 offset:4640
	s_waitcnt lgkmcnt(2)
	v_mfma_f32_32x32x16_bf16 v[16:31], v[176:179], v[64:67], v[16:31]
	ds_read_b128 v[176:179], v173 offset:9248
	v_mfma_f32_32x32x16_bf16 v[0:15], v[226:229], v[64:67], v[0:15]
	ds_read_b128 v[226:229], v173 offset:13856
	ds_read_b128 v[202:205], v174 offset:12800
	ds_read_b128 v[206:209], v174 offset:12832
	ds_read_b128 v[210:213], v174 offset:12864
	ds_read_b128 v[214:217], v174 offset:12896
	ds_read_b128 v[218:221], v174 offset:12928
	ds_read_b128 v[222:225], v174 offset:12960
	s_cmp_gt_i32 s33, s97
	s_cbranch_scc1 .Lat_mask_a_0

.Lat_skip_ld_0:
	s_add_i32 s4, s52, 1
	s_cmp_lg_u32 s52, 2
	s_cselect_b32 s52, s4, 0
	s_add_i32 s33, s33, 64
	v_subrev_u32_e32 v197, 64, v197
	v_add_u32_e32 v173, 0xc840, v234
	s_mov_b32 s0, s54
	s_cmp_eq_u32 s53, s54
	s_waitcnt lgkmcnt(0)
	s_barrier
	s_cbranch_scc1 .Lat_tail
	s_add_i32 s54, s0, 1
	v_add_u32_e32 v174, 0x6400, v196
	s_mul_i32 s4, s52, 0x4800
	v_add_u32_e32 v234, s4, v195
	ds_read_b128 v[202:205], v174 offset:0
	ds_read_b128 v[206:209], v174 offset:32
	ds_read_b128 v[210:213], v174 offset:64
	ds_read_b128 v[214:217], v174 offset:96
	ds_read_b128 v[218:221], v174 offset:128
	ds_read_b128 v[222:225], v174 offset:160
	v_fma_f32 v64, v64, s84, -v199
	v_exp_f32_e32 v64, v64
	v_fma_f32 v65, v65, s84, -v199
	v_exp_f32_e32 v65, v65
	v_add_f32_e32 v200, v200, v64
	v_fma_f32 v66, v66, s84, -v199
	v_exp_f32_e32 v66, v66
	v_add_f32_e32 v200, v200, v65
	s_waitcnt lgkmcnt(4)
	v_mfma_f32_32x32x16_bf16 v[80:95], v[202:205], v[96:99], 0
	ds_read_b128 v[202:205], v174 offset:192
	v_fma_f32 v67, v67, s84, -v199
	v_exp_f32_e32 v67, v67
	v_add_f32_e32 v200, v200, v66
	v_fma_f32 v68, v68, s84, -v199
	v_mfma_f32_32x32x16_bf16 v[80:95], v[206:209], v[100:103], v[80:95]
	ds_read_b128 v[206:209], v174 offset:224
	v_exp_f32_e32 v68, v68
	v_add_f32_e32 v200, v200, v67
	v_fma_f32 v69, v69, s84, -v199
	v_exp_f32_e32 v69, v69
	s_waitcnt lgkmcnt(4)
	v_mfma_f32_32x32x16_bf16 v[80:95], v[210:213], v[104:107], v[80:95]
	ds_read_b128 v[210:213], v174 offset:256
	v_add_f32_e32 v200, v200, v68
	v_fma_f32 v70, v70, s84, -v199
	v_exp_f32_e32 v70, v70
	v_add_f32_e32 v200, v200, v69
	v_mfma_f32_32x32x16_bf16 v[80:95], v[214:217], v[108:111], v[80:95]
	ds_read_b128 v[214:217], v174 offset:288
	v_fma_f32 v71, v71, s84, -v199
	v_exp_f32_e32 v71, v71
	v_add_f32_e32 v200, v200, v70
	v_fma_f32 v72, v72, s84, -v199
	s_waitcnt lgkmcnt(4)
	v_mfma_f32_32x32x16_bf16 v[80:95], v[218:221], v[112:115], v[80:95]
	ds_read_b128 v[218:221], v174 offset:320
	v_exp_f32_e32 v72, v72
	v_add_f32_e32 v200, v200, v71
	v_fma_f32 v73, v73, s84, -v199
	v_exp_f32_e32 v73, v73
	v_mfma_f32_32x32x16_bf16 v[80:95], v[222:225], v[116:119], v[80:95]
	ds_read_b128 v[222:225], v174 offset:352
	v_add_f32_e32 v200, v200, v72
	v_fma_f32 v74, v74, s84, -v199
	v_exp_f32_e32 v74, v74
	v_add_f32_e32 v200, v200, v73
	s_waitcnt lgkmcnt(4)
	v_mfma_f32_32x32x16_bf16 v[80:95], v[202:205], v[120:123], v[80:95]
	ds_read_b128 v[164:167], v173 offset:0
	v_fma_f32 v75, v75, s84, -v199
	v_exp_f32_e32 v75, v75
	v_add_f32_e32 v200, v200, v74
	v_fma_f32 v76, v76, s84, -v199
	v_mfma_f32_32x32x16_bf16 v[80:95], v[206:209], v[124:127], v[80:95]
	ds_read_b128 v[168:171], v173 offset:4608
	v_exp_f32_e32 v76, v76
	v_add_f32_e32 v200, v200, v75
	v_fma_f32 v77, v77, s84, -v199
	v_exp_f32_e32 v77, v77
	s_waitcnt lgkmcnt(4)
	v_mfma_f32_32x32x16_bf16 v[80:95], v[210:213], v[160:163], v[80:95]
	ds_read_b128 v[176:179], v173 offset:9216
	v_add_f32_e32 v200, v200, v76
	v_fma_f32 v78, v78, s84, -v199
	v_exp_f32_e32 v78, v78
	v_add_f32_e32 v200, v200, v77
	v_mfma_f32_32x32x16_bf16 v[80:95], v[214:217], v[152:155], v[80:95]
	ds_read_b128 v[226:229], v173 offset:13824
	v_fma_f32 v79, v79, s84, -v199
	v_exp_f32_e32 v79, v79
	v_add_f32_e32 v200, v200, v78
	v_add_f32_e32 v200, v200, v79
	s_waitcnt lgkmcnt(4)
	v_mfma_f32_32x32x16_bf16 v[80:95], v[218:221], v[156:159], v[80:95]
	v_cvt_pk_bf16_f32 v64, v64, v65
	v_cvt_pk_bf16_f32 v65, v66, v67
	v_cvt_pk_bf16_f32 v66, v68, v69
	v_cvt_pk_bf16_f32 v67, v70, v71
	v_mfma_f32_32x32x16_bf16 v[80:95], v[222:225], v[148:151], v[80:95]
	v_cvt_pk_bf16_f32 v68, v72, v73
	v_cvt_pk_bf16_f32 v69, v74, v75
	v_cvt_pk_bf16_f32 v70, v76, v77
	v_cvt_pk_bf16_f32 v71, v78, v79
	s_waitcnt lgkmcnt(2)
	v_mfma_f32_32x32x16_bf16 v[48:63], v[164:167], v[64:67], v[48:63]
	ds_read_b128 v[164:167], v173 offset:32
	v_mfma_f32_32x32x16_bf16 v[32:47], v[168:171], v[64:67], v[32:47]
	ds_read_b128 v[168:171], v173 offset:4640
	s_waitcnt lgkmcnt(2)
	v_mfma_f32_32x32x16_bf16 v[16:31], v[176:179], v[64:67], v[16:31]
	ds_read_b128 v[176:179], v173 offset:9248
	v_mfma_f32_32x32x16_bf16 v[0:15], v[226:229], v[64:67], v[0:15]
	ds_read_b128 v[226:229], v173 offset:13856
	ds_read_b128 v[202:205], v174 offset:12800
	ds_read_b128 v[206:209], v174 offset:12832
	ds_read_b128 v[210:213], v174 offset:12864
	ds_read_b128 v[214:217], v174 offset:12896
	ds_read_b128 v[218:221], v174 offset:12928
	ds_read_b128 v[222:225], v174 offset:12960
	s_cmp_gt_i32 s33, s97
	s_cbranch_scc1 .Lat_mask_a_1
